# attention tile loops (5 of 7): V-fragment LDS reads issued 5-deep through the PV MFMA chain using dead K quads
# baseline (speedup 1.0000x reference)
; #define LAS __attribute__((address_space(3)))
; DI unsigned cvtpk(float lo, float hi) { f32x2_t v = {lo, hi}; bf16x2_t b = __builtin_convertvector(v, bf16x2_t); return __builtin_bit_cast(unsigned, b); }
; DI float fexp2(float x) { return __builtin_amdgcn_exp2f(x); }
; #define MFMA32(a, b, c) __builtin_amdgcn_mfma_f32_32x32x16_bf16((a), (b), (c), 0, 0, 0)
;     ...
;             const float mu = (m == -INFINITY) ? 0.f : m;
;             float rs = 0.f;
; #pragma unroll
;             for (int i = 0; i < 16; i += 2) {
;                 f32x2_t a2 = {s0[i], s0[i + 1]}, b2 = {s1[i], s1[i + 1]}; const f32x2_t nm = {-mu, -mu};
;                 a2 = a2 + nm; b2 = b2 + nm;
;                 s0[i] = fexp2(a2.x); s0[i + 1] = fexp2(a2.y); s1[i] = fexp2(b2.x); s1[i + 1] = fexp2(b2.y);
;                 rs += (s0[i] + s0[i + 1]) + (s1[i] + s1[i + 1]); }
;             l += rs;
;             bf16x8 pb[4];
;             { u32x4 p; p.x = cvtpk(s0[0], s0[1]); p.y = cvtpk(s0[2], s0[3]); p.z = cvtpk(s0[4], s0[5]); p.w = cvtpk(s0[6], s0[7]); pb[0] = __builtin_bit_cast(bf16x8, p);
;               p.x = cvtpk(s0[8], s0[9]); p.y = cvtpk(s0[10], s0[11]); p.z = cvtpk(s0[12], s0[13]); p.w = cvtpk(s0[14], s0[15]); pb[1] = __builtin_bit_cast(bf16x8, p);
;               p.x = cvtpk(s1[0], s1[1]); p.y = cvtpk(s1[2], s1[3]); p.z = cvtpk(s1[4], s1[5]); p.w = cvtpk(s1[6], s1[7]); pb[2] = __builtin_bit_cast(bf16x8, p);
;               p.x = cvtpk(s1[8], s1[9]); p.y = cvtpk(s1[10], s1[11]); p.z = cvtpk(s1[12], s1[13]); p.w = cvtpk(s1[14], s1[15]); pb[3] = __builtin_bit_cast(bf16x8, p); }
;             const LAS unsigned char* vb = bb + KB + n * PV + 8 * h;
; #pragma unroll
;             for (int sx = 0; sx < 4; ++sx) {
;                 const s16x4 a0 = *(const LAS s16x4*)(vb + 32 * sx), a1 = *(const LAS s16x4*)(vb + 32 * sx + 16);
;                 const s16x4 b0 = *(const LAS s16x4*)(vb + 32 * PV + 32 * sx), b1 = *(const LAS s16x4*)(vb + 32 * PV + 32 * sx + 16);
;                 o0 = MFMA32(__builtin_shufflevector(a0, a1, 0, 1, 2, 3, 4, 5, 6, 7), pb[sx], o0);
;                 o1 = MFMA32(__builtin_shufflevector(b0, b1, 0, 1, 2, 3, 4, 5, 6, 7), pb[sx], o1);
;             }
.LBB0_196:
	v_cmp_neq_f32_e32 vcc, s79, v115
	s_nop 1
	v_cndmask_b32_e64 v116, v247, -v115, vcc
	v_pk_add_f32 v[34:35], v[34:35], v[116:117] op_sel_hi:[1,0]
	v_pk_add_f32 v[50:51], v[50:51], v[116:117] op_sel_hi:[1,0]
	v_pk_add_f32 v[36:37], v[36:37], v[116:117] op_sel_hi:[1,0]
	v_pk_add_f32 v[52:53], v[52:53], v[116:117] op_sel_hi:[1,0]
	v_exp_f32_e32 v119, v34
	v_exp_f32_e32 v35, v35
	v_exp_f32_e32 v121, v50
	v_exp_f32_e32 v51, v51
	v_exp_f32_e32 v118, v36
	v_exp_f32_e32 v34, v37
	v_exp_f32_e32 v120, v52
	v_exp_f32_e32 v50, v53
	v_pk_add_f32 v[38:39], v[38:39], v[116:117] op_sel_hi:[1,0]
	v_pk_add_f32 v[36:37], v[34:35], v[118:119]
	v_exp_f32_e32 v123, v39
	v_pk_add_f32 v[52:53], v[50:51], v[120:121]
	v_pk_add_f32 v[40:41], v[40:41], v[116:117] op_sel_hi:[1,0]
	v_pk_add_f32 v[36:37], v[52:53], v[36:37]
	v_pk_add_f32 v[52:53], v[54:55], v[116:117] op_sel_hi:[1,0]
	v_exp_f32_e32 v55, v38
	v_exp_f32_e32 v54, v52
	v_exp_f32_e32 v122, v53
	v_pk_add_f32 v[52:53], v[56:57], v[116:117] op_sel_hi:[1,0]
	v_add_f32_e32 v37, 0, v37
	v_exp_f32_e32 v126, v40
	v_pk_add_f32 v[38:39], v[122:123], v[54:55]
	v_exp_f32_e32 v127, v41
	v_pk_add_f32 v[38:39], v[38:39], v[38:39] op_sel_hi:[0,1]
	v_exp_f32_e32 v128, v52
	v_exp_f32_e32 v129, v53
	v_pk_add_f32 v[40:41], v[42:43], v[116:117] op_sel_hi:[1,0]
	v_pk_add_f32 v[42:43], v[58:59], v[116:117] op_sel_hi:[1,0]
	v_add_f32_e32 v37, v36, v37
	v_exp_f32_e32 v36, v40
	v_exp_f32_e32 v38, v41
	v_exp_f32_e32 v52, v42
	v_exp_f32_e32 v56, v43
	v_add_f32_e32 v53, v127, v126
	v_add_f32_e32 v57, v129, v128
	v_pk_add_f32 v[40:41], v[38:39], v[36:37]
	v_pk_add_f32 v[42:43], v[56:57], v[52:53]
	s_nop 0
	v_pk_add_f32 v[40:41], v[42:43], v[40:41]
	v_pk_add_f32 v[42:43], v[44:45], v[116:117] op_sel_hi:[1,0]
	v_pk_add_f32 v[44:45], v[60:61], v[116:117] op_sel_hi:[1,0]
	v_exp_f32_e32 v59, v42
	v_exp_f32_e32 v61, v43
	v_exp_f32_e32 v58, v44
	v_exp_f32_e32 v60, v45
	v_pk_add_f32 v[44:45], v[62:63], v[116:117] op_sel_hi:[1,0]
	v_pk_add_f32 v[40:41], v[40:41], v[40:41] op_sel_hi:[0,1]
	v_exp_f32_e32 v53, v44
	v_exp_f32_e32 v57, v45
	v_pk_add_f32 v[42:43], v[60:61], v[58:59]
	s_nop 0
	v_pk_add_f32 v[124:125], v[42:43], v[42:43] op_sel_hi:[0,1]
	v_pk_add_f32 v[42:43], v[46:47], v[116:117] op_sel_hi:[1,0]
	v_add_f32_e32 v117, v57, v53
	v_exp_f32_e32 v37, v42
	v_exp_f32_e32 v39, v43
	v_pk_add_f32 v[42:43], v[48:49], v[116:117] op_sel_hi:[1,0]
	v_pk_add_f32 v[44:45], v[64:65], v[116:117] op_sel_hi:[1,0]
	v_exp_f32_e32 v40, v42
	v_exp_f32_e32 v124, v43
	v_exp_f32_e32 v62, v44
	v_exp_f32_e32 v116, v45
	v_add_f32_e32 v63, v39, v37
	v_pk_add_f32 v[42:43], v[124:125], v[40:41]
	v_cvt_pk_bf16_f32 v47, v118, v34
	v_pk_add_f32 v[44:45], v[116:117], v[62:63]
	v_cvt_pk_bf16_f32 v34, v52, v56
	v_pk_add_f32 v[42:43], v[44:45], v[42:43]
	v_cvt_pk_bf16_f32 v45, v40, v124
	v_cvt_pk_bf16_f32 v40, v54, v122
	v_add3_u32 v54, s4, v188, v164
	v_cvt_pk_bf16_f32 v44, v37, v39
	v_cvt_pk_bf16_f32 v37, v62, v116
	v_add_u32_e32 v62, 0x3000, v54
	v_add_f32_e32 v41, v42, v43
	v_cvt_pk_bf16_f32 v42, v36, v38
	v_cvt_pk_bf16_f32 v38, v121, v51
	v_cvt_pk_bf16_f32 v39, v120, v50
	v_cvt_pk_bf16_f32 v36, v53, v57
	ds_read2_b64 v[50:53], v62 offset0:160 offset1:162
	v_add_u32_e32 v63, 0x2000, v54
	v_cvt_pk_bf16_f32 v46, v119, v35
	v_cvt_pk_bf16_f32 v48, v55, v123
	v_cvt_pk_bf16_f32 v43, v59, v61
	v_cvt_pk_bf16_f32 v35, v58, v60
	ds_read2_b64 v[54:57], v63 offset0:128 offset1:130
	ds_read2_b64 v[58:61], v63 offset0:132 offset1:134
	v_cvt_pk_bf16_f32 v49, v126, v127
	v_add_f32_e32 v113, v113, v41
	v_cvt_pk_bf16_f32 v41, v128, v129
	ds_read2_b64 v[116:119], v62 offset0:164 offset1:166
	ds_read2_b64 v[120:123], v63 offset0:136 offset1:138
	s_waitcnt lgkmcnt(3)
	v_mfma_f32_32x32x16_bf16 v[18:33], v[54:57], v[46:49], v[18:33]
	v_mfma_f32_32x32x16_bf16 v[2:17], v[50:53], v[46:49], v[2:17]
	ds_read2_b64 v[54:57], v62 offset0:168 offset1:170
	ds_read2_b64 v[50:53], v63 offset0:140 offset1:142
	s_waitcnt lgkmcnt(4)
	v_mfma_f32_32x32x16_bf16 v[18:33], v[58:61], v[42:45], v[18:33]
	ds_read2_b64 v[58:61], v62 offset0:172 offset1:174
	s_waitcnt lgkmcnt(4)
	v_mfma_f32_32x32x16_bf16 v[2:17], v[116:119], v[42:45], v[2:17]
	s_waitcnt lgkmcnt(3)
	v_mfma_f32_32x32x16_bf16 v[18:33], v[120:123], v[38:41], v[18:33]
	s_waitcnt lgkmcnt(2)
	v_mfma_f32_32x32x16_bf16 v[2:17], v[54:57], v[38:41], v[2:17]
	s_waitcnt lgkmcnt(1)
	v_mfma_f32_32x32x16_bf16 v[18:33], v[50:53], v[34:37], v[18:33]
	s_waitcnt lgkmcnt(0)
	v_mfma_f32_32x32x16_bf16 v[2:17], v[58:61], v[34:37], v[2:17]
	s_cmp_ge_i32 s8, s14
	s_mov_b64 s[4:5], -1
	s_cbranch_scc0 .LBB0_190

; #define LAS __attribute__((address_space(3)))
; DI unsigned cvtpk(float lo, float hi) { f32x2_t v = {lo, hi}; bf16x2_t b = __builtin_convertvector(v, bf16x2_t); return __builtin_bit_cast(unsigned, b); }
; DI float fexp2(float x) { return __builtin_amdgcn_exp2f(x); }
; #define MFMA32(a, b, c) __builtin_amdgcn_mfma_f32_32x32x16_bf16((a), (b), (c), 0, 0, 0)
;     ...
;             const float mu = (m == -INFINITY) ? 0.f : m;
;             float rs = 0.f;
; #pragma unroll
;             for (int i = 0; i < 16; i += 2) {
;                 f32x2_t a2 = {s0[i], s0[i + 1]}, b2 = {s1[i], s1[i + 1]}; const f32x2_t nm = {-mu, -mu};
;                 a2 = a2 + nm; b2 = b2 + nm;
;                 s0[i] = fexp2(a2.x); s0[i + 1] = fexp2(a2.y); s1[i] = fexp2(b2.x); s1[i + 1] = fexp2(b2.y);
;                 rs += (s0[i] + s0[i + 1]) + (s1[i] + s1[i + 1]); }
;             l += rs;
;             bf16x8 pb[4];
;             { u32x4 p; p.x = cvtpk(s0[0], s0[1]); p.y = cvtpk(s0[2], s0[3]); p.z = cvtpk(s0[4], s0[5]); p.w = cvtpk(s0[6], s0[7]); pb[0] = __builtin_bit_cast(bf16x8, p);
;               p.x = cvtpk(s0[8], s0[9]); p.y = cvtpk(s0[10], s0[11]); p.z = cvtpk(s0[12], s0[13]); p.w = cvtpk(s0[14], s0[15]); pb[1] = __builtin_bit_cast(bf16x8, p);
;               p.x = cvtpk(s1[0], s1[1]); p.y = cvtpk(s1[2], s1[3]); p.z = cvtpk(s1[4], s1[5]); p.w = cvtpk(s1[6], s1[7]); pb[2] = __builtin_bit_cast(bf16x8, p);
;               p.x = cvtpk(s1[8], s1[9]); p.y = cvtpk(s1[10], s1[11]); p.z = cvtpk(s1[12], s1[13]); p.w = cvtpk(s1[14], s1[15]); pb[3] = __builtin_bit_cast(bf16x8, p); }
;             const LAS unsigned char* vb = bb + KB + n * PV + 8 * h;
; #pragma unroll
;             for (int sx = 0; sx < 4; ++sx) {
;                 const s16x4 a0 = *(const LAS s16x4*)(vb + 32 * sx), a1 = *(const LAS s16x4*)(vb + 32 * sx + 16);
;                 const s16x4 b0 = *(const LAS s16x4*)(vb + 32 * PV + 32 * sx), b1 = *(const LAS s16x4*)(vb + 32 * PV + 32 * sx + 16);
;                 o0 = MFMA32(__builtin_shufflevector(a0, a1, 0, 1, 2, 3, 4, 5, 6, 7), pb[sx], o0);
;                 o1 = MFMA32(__builtin_shufflevector(b0, b1, 0, 1, 2, 3, 4, 5, 6, 7), pb[sx], o1);
;             }
.LBB0_253:
	v_cmp_neq_f32_e32 vcc, s79, v145
	s_nop 1
	v_cndmask_b32_e64 v146, v247, -v145, vcc
	v_pk_add_f32 v[50:51], v[50:51], v[146:147] op_sel_hi:[1,0]
	v_pk_add_f32 v[34:35], v[34:35], v[146:147] op_sel_hi:[1,0]
	v_pk_add_f32 v[52:53], v[52:53], v[146:147] op_sel_hi:[1,0]
	v_pk_add_f32 v[36:37], v[36:37], v[146:147] op_sel_hi:[1,0]
	v_exp_f32_e32 v149, v50
	v_exp_f32_e32 v51, v51
	v_exp_f32_e32 v151, v34
	v_exp_f32_e32 v35, v35
	v_exp_f32_e32 v148, v52
	v_exp_f32_e32 v50, v53
	v_exp_f32_e32 v150, v36
	v_exp_f32_e32 v34, v37
	v_pk_add_f32 v[38:39], v[38:39], v[146:147] op_sel_hi:[1,0]
	v_pk_add_f32 v[36:37], v[50:51], v[148:149]
	v_pk_add_f32 v[56:57], v[56:57], v[146:147] op_sel_hi:[1,0]
	v_pk_add_f32 v[52:53], v[34:35], v[150:151]
	v_pk_add_f32 v[40:41], v[40:41], v[146:147] op_sel_hi:[1,0]
	v_pk_add_f32 v[36:37], v[52:53], v[36:37]
	v_pk_add_f32 v[52:53], v[54:55], v[146:147] op_sel_hi:[1,0]
	v_exp_f32_e32 v54, v38
	v_exp_f32_e32 v55, v52
	v_exp_f32_e32 v53, v53
	v_exp_f32_e32 v52, v39
	v_add_f32_e32 v37, 0, v37
	v_exp_f32_e32 v156, v56
	v_exp_f32_e32 v157, v57
	v_pk_add_f32 v[38:39], v[52:53], v[54:55]
	v_exp_f32_e32 v158, v40
	v_pk_add_f32 v[38:39], v[38:39], v[38:39] op_sel_hi:[0,1]
	v_exp_f32_e32 v159, v41
	v_pk_add_f32 v[40:41], v[58:59], v[146:147] op_sel_hi:[1,0]
	v_pk_add_f32 v[42:43], v[42:43], v[146:147] op_sel_hi:[1,0]
	v_add_f32_e32 v37, v36, v37
	v_exp_f32_e32 v36, v40
	v_exp_f32_e32 v38, v41
	v_exp_f32_e32 v56, v42
	v_exp_f32_e32 v152, v43
	v_add_f32_e32 v57, v157, v156
	v_add_f32_e32 v153, v159, v158
	v_pk_add_f32 v[40:41], v[38:39], v[36:37]
	v_pk_add_f32 v[42:43], v[152:153], v[56:57]
	v_pk_add_f32 v[44:45], v[44:45], v[146:147] op_sel_hi:[1,0]
	v_pk_add_f32 v[40:41], v[42:43], v[40:41]
	v_pk_add_f32 v[42:43], v[60:61], v[146:147] op_sel_hi:[1,0]
	v_exp_f32_e32 v58, v44
	v_exp_f32_e32 v59, v42
	v_exp_f32_e32 v61, v43
	v_exp_f32_e32 v60, v45
	v_pk_add_f32 v[44:45], v[46:47], v[146:147] op_sel_hi:[1,0]
	v_pk_add_f32 v[40:41], v[40:41], v[40:41] op_sel_hi:[0,1]
	v_exp_f32_e32 v57, v44
	v_exp_f32_e32 v153, v45
	v_pk_add_f32 v[42:43], v[60:61], v[58:59]
	v_cvt_pk_bf16_f32 v46, v149, v51
	v_pk_add_f32 v[154:155], v[42:43], v[42:43] op_sel_hi:[0,1]
	v_pk_add_f32 v[42:43], v[62:63], v[146:147] op_sel_hi:[1,0]
	v_add_f32_e32 v147, v153, v57
	v_exp_f32_e32 v37, v42
	v_exp_f32_e32 v39, v43
	v_pk_add_f32 v[42:43], v[64:65], v[146:147] op_sel_hi:[1,0]
	v_pk_add_f32 v[44:45], v[48:49], v[146:147] op_sel_hi:[1,0]
	v_exp_f32_e32 v40, v42
	v_exp_f32_e32 v154, v43
	v_exp_f32_e32 v62, v44
	v_exp_f32_e32 v146, v45
	v_add_f32_e32 v63, v39, v37
	v_pk_add_f32 v[42:43], v[154:155], v[40:41]
	v_cvt_pk_bf16_f32 v47, v148, v50
	v_pk_add_f32 v[44:45], v[146:147], v[62:63]
	v_cvt_pk_bf16_f32 v48, v55, v53
	v_pk_add_f32 v[42:43], v[44:45], v[42:43]
	v_cvt_pk_bf16_f32 v45, v40, v154
	v_cvt_pk_bf16_f32 v40, v54, v52
	v_add3_u32 v54, s10, v119, v116
	v_cvt_pk_bf16_f32 v44, v37, v39
	v_cvt_pk_bf16_f32 v37, v62, v146
	v_add_u32_e32 v62, 0x5000, v54
	ds_read2_b64 v[50:53], v62 offset0:160 offset1:162
	v_add_u32_e32 v63, 0x4000, v54
	v_add_f32_e32 v41, v42, v43
	v_cvt_pk_bf16_f32 v42, v36, v38
	v_cvt_pk_bf16_f32 v43, v59, v61
	v_cvt_pk_bf16_f32 v38, v151, v35
	v_cvt_pk_bf16_f32 v39, v150, v34
	v_cvt_pk_bf16_f32 v34, v56, v152
	v_cvt_pk_bf16_f32 v35, v58, v60
	v_cvt_pk_bf16_f32 v36, v57, v153
	ds_read2_b64 v[54:57], v63 offset0:128 offset1:130
	ds_read2_b64 v[58:61], v63 offset0:132 offset1:134
	v_cvt_pk_bf16_f32 v49, v156, v157
	v_add_f32_e32 v144, v144, v41
	v_cvt_pk_bf16_f32 v41, v158, v159
	ds_read2_b64 v[146:149], v62 offset0:164 offset1:166
	ds_read2_b64 v[150:153], v63 offset0:136 offset1:138
	s_waitcnt lgkmcnt(3)
	v_mfma_f32_32x32x16_bf16 v[18:33], v[54:57], v[46:49], v[18:33]
	v_mfma_f32_32x32x16_bf16 v[2:17], v[50:53], v[46:49], v[2:17]
	ds_read2_b64 v[54:57], v62 offset0:168 offset1:170
	ds_read2_b64 v[50:53], v63 offset0:140 offset1:142
	s_waitcnt lgkmcnt(4)
	v_mfma_f32_32x32x16_bf16 v[18:33], v[58:61], v[42:45], v[18:33]
	ds_read2_b64 v[58:61], v62 offset0:172 offset1:174
	s_waitcnt lgkmcnt(4)
	v_mfma_f32_32x32x16_bf16 v[2:17], v[146:149], v[42:45], v[2:17]
	s_waitcnt lgkmcnt(3)
	v_mfma_f32_32x32x16_bf16 v[18:33], v[150:153], v[38:41], v[18:33]
	s_waitcnt lgkmcnt(2)
	v_mfma_f32_32x32x16_bf16 v[2:17], v[54:57], v[38:41], v[2:17]
	s_waitcnt lgkmcnt(1)
	v_mfma_f32_32x32x16_bf16 v[18:33], v[50:53], v[34:37], v[18:33]
	s_waitcnt lgkmcnt(0)
	v_mfma_f32_32x32x16_bf16 v[2:17], v[58:61], v[34:37], v[2:17]
	s_cmp_ge_u32 s45, s37
	s_cbranch_scc1 .LBB0_259

; #define LAS __attribute__((address_space(3)))
; DI unsigned cvtpk(float lo, float hi) { f32x2_t v = {lo, hi}; bf16x2_t b = __builtin_convertvector(v, bf16x2_t); return __builtin_bit_cast(unsigned, b); }
; DI float fexp2(float x) { return __builtin_amdgcn_exp2f(x); }
; #define MFMA32(a, b, c) __builtin_amdgcn_mfma_f32_32x32x16_bf16((a), (b), (c), 0, 0, 0)
;     ...
;             const float mu = (m == -INFINITY) ? 0.f : m;
;             float rs = 0.f;
; #pragma unroll
;             for (int i = 0; i < 16; i += 2) {
;                 f32x2_t a2 = {s0[i], s0[i + 1]}, b2 = {s1[i], s1[i + 1]}; const f32x2_t nm = {-mu, -mu};
;                 a2 = a2 + nm; b2 = b2 + nm;
;                 s0[i] = fexp2(a2.x); s0[i + 1] = fexp2(a2.y); s1[i] = fexp2(b2.x); s1[i + 1] = fexp2(b2.y);
;                 rs += (s0[i] + s0[i + 1]) + (s1[i] + s1[i + 1]); }
;             l += rs;
;             bf16x8 pb[4];
;             { u32x4 p; p.x = cvtpk(s0[0], s0[1]); p.y = cvtpk(s0[2], s0[3]); p.z = cvtpk(s0[4], s0[5]); p.w = cvtpk(s0[6], s0[7]); pb[0] = __builtin_bit_cast(bf16x8, p);
;               p.x = cvtpk(s0[8], s0[9]); p.y = cvtpk(s0[10], s0[11]); p.z = cvtpk(s0[12], s0[13]); p.w = cvtpk(s0[14], s0[15]); pb[1] = __builtin_bit_cast(bf16x8, p);
;               p.x = cvtpk(s1[0], s1[1]); p.y = cvtpk(s1[2], s1[3]); p.z = cvtpk(s1[4], s1[5]); p.w = cvtpk(s1[6], s1[7]); pb[2] = __builtin_bit_cast(bf16x8, p);
;               p.x = cvtpk(s1[8], s1[9]); p.y = cvtpk(s1[10], s1[11]); p.z = cvtpk(s1[12], s1[13]); p.w = cvtpk(s1[14], s1[15]); pb[3] = __builtin_bit_cast(bf16x8, p); }
;             const LAS unsigned char* vb = bb + KB + n * PV + 8 * h;
; #pragma unroll
;             for (int sx = 0; sx < 4; ++sx) {
;                 const s16x4 a0 = *(const LAS s16x4*)(vb + 32 * sx), a1 = *(const LAS s16x4*)(vb + 32 * sx + 16);
;                 const s16x4 b0 = *(const LAS s16x4*)(vb + 32 * PV + 32 * sx), b1 = *(const LAS s16x4*)(vb + 32 * PV + 32 * sx + 16);
;                 o0 = MFMA32(__builtin_shufflevector(a0, a1, 0, 1, 2, 3, 4, 5, 6, 7), pb[sx], o0);
;                 o1 = MFMA32(__builtin_shufflevector(b0, b1, 0, 1, 2, 3, 4, 5, 6, 7), pb[sx], o1);
;             }
.LBB0_319:
	v_cmp_neq_f32_e32 vcc, s79, v112
	s_nop 1
	v_cndmask_b32_e64 v124, v247, -v112, vcc
	v_pk_add_f32 v[50:51], v[50:51], v[124:125] op_sel_hi:[1,0]
	v_pk_add_f32 v[34:35], v[34:35], v[124:125] op_sel_hi:[1,0]
	v_pk_add_f32 v[52:53], v[52:53], v[124:125] op_sel_hi:[1,0]
	v_pk_add_f32 v[36:37], v[36:37], v[124:125] op_sel_hi:[1,0]
	v_exp_f32_e32 v127, v50
	v_exp_f32_e32 v51, v51
	v_exp_f32_e32 v129, v34
	v_exp_f32_e32 v35, v35
	v_exp_f32_e32 v126, v52
	v_exp_f32_e32 v50, v53
	v_exp_f32_e32 v128, v36
	v_exp_f32_e32 v34, v37
	v_pk_add_f32 v[38:39], v[38:39], v[124:125] op_sel_hi:[1,0]
	v_pk_add_f32 v[36:37], v[50:51], v[126:127]
	v_pk_add_f32 v[56:57], v[56:57], v[124:125] op_sel_hi:[1,0]
	v_pk_add_f32 v[52:53], v[34:35], v[128:129]
	v_pk_add_f32 v[40:41], v[40:41], v[124:125] op_sel_hi:[1,0]
	v_pk_add_f32 v[36:37], v[52:53], v[36:37]
	v_pk_add_f32 v[52:53], v[54:55], v[124:125] op_sel_hi:[1,0]
	v_exp_f32_e32 v54, v38
	v_exp_f32_e32 v55, v52
	v_exp_f32_e32 v53, v53
	v_exp_f32_e32 v52, v39
	v_add_f32_e32 v37, 0, v37
	v_exp_f32_e32 v123, v56
	v_exp_f32_e32 v134, v57
	v_pk_add_f32 v[38:39], v[52:53], v[54:55]
	v_exp_f32_e32 v135, v40
	v_pk_add_f32 v[38:39], v[38:39], v[38:39] op_sel_hi:[0,1]
	v_exp_f32_e32 v136, v41
	v_pk_add_f32 v[40:41], v[58:59], v[124:125] op_sel_hi:[1,0]
	v_pk_add_f32 v[42:43], v[42:43], v[124:125] op_sel_hi:[1,0]
	v_add_f32_e32 v37, v36, v37
	v_exp_f32_e32 v36, v40
	v_exp_f32_e32 v38, v41
	v_exp_f32_e32 v56, v42
	v_exp_f32_e32 v130, v43
	v_add_f32_e32 v57, v134, v123
	v_add_f32_e32 v131, v136, v135
	v_pk_add_f32 v[40:41], v[38:39], v[36:37]
	v_pk_add_f32 v[42:43], v[130:131], v[56:57]
	v_pk_add_f32 v[44:45], v[44:45], v[124:125] op_sel_hi:[1,0]
	v_pk_add_f32 v[40:41], v[42:43], v[40:41]
	v_pk_add_f32 v[42:43], v[60:61], v[124:125] op_sel_hi:[1,0]
	v_exp_f32_e32 v58, v44
	v_exp_f32_e32 v59, v42
	v_exp_f32_e32 v61, v43
	v_exp_f32_e32 v60, v45
	v_pk_add_f32 v[44:45], v[46:47], v[124:125] op_sel_hi:[1,0]
	v_pk_add_f32 v[40:41], v[40:41], v[40:41] op_sel_hi:[0,1]
	v_exp_f32_e32 v57, v44
	v_exp_f32_e32 v131, v45
	v_pk_add_f32 v[42:43], v[60:61], v[58:59]
	v_cvt_pk_bf16_f32 v46, v127, v51
	v_pk_add_f32 v[132:133], v[42:43], v[42:43] op_sel_hi:[0,1]
	v_pk_add_f32 v[42:43], v[62:63], v[124:125] op_sel_hi:[1,0]
	v_add_f32_e32 v125, v131, v57
	v_exp_f32_e32 v37, v42
	v_exp_f32_e32 v39, v43
	v_pk_add_f32 v[42:43], v[64:65], v[124:125] op_sel_hi:[1,0]
	v_pk_add_f32 v[44:45], v[48:49], v[124:125] op_sel_hi:[1,0]
	v_exp_f32_e32 v40, v42
	v_exp_f32_e32 v132, v43
	v_exp_f32_e32 v62, v44
	v_exp_f32_e32 v124, v45
	v_add_f32_e32 v63, v39, v37
	v_pk_add_f32 v[42:43], v[132:133], v[40:41]
	v_cvt_pk_bf16_f32 v47, v126, v50
	v_pk_add_f32 v[44:45], v[124:125], v[62:63]
	v_cvt_pk_bf16_f32 v48, v55, v53
	v_pk_add_f32 v[42:43], v[44:45], v[42:43]
	v_cvt_pk_bf16_f32 v45, v40, v132
	v_cvt_pk_bf16_f32 v40, v54, v52
	v_add3_u32 v54, s36, v119, v116
	v_cvt_pk_bf16_f32 v44, v37, v39
	v_cvt_pk_bf16_f32 v37, v62, v124
	v_add_u32_e32 v62, 0x3000, v54
	ds_read2_b64 v[50:53], v62 offset0:160 offset1:162
	v_add_u32_e32 v63, 0x2000, v54
	v_add_f32_e32 v41, v42, v43
	v_cvt_pk_bf16_f32 v42, v36, v38
	v_cvt_pk_bf16_f32 v43, v59, v61
	v_cvt_pk_bf16_f32 v38, v129, v35
	v_cvt_pk_bf16_f32 v39, v128, v34
	v_cvt_pk_bf16_f32 v34, v56, v130
	v_cvt_pk_bf16_f32 v35, v58, v60
	v_cvt_pk_bf16_f32 v36, v57, v131
	ds_read2_b64 v[54:57], v63 offset0:128 offset1:130
	ds_read2_b64 v[58:61], v63 offset0:132 offset1:134
	v_cvt_pk_bf16_f32 v49, v123, v134
	v_add_f32_e32 v105, v105, v41
	v_cvt_pk_bf16_f32 v41, v135, v136
	ds_read2_b64 v[124:127], v62 offset0:164 offset1:166
	ds_read2_b64 v[128:131], v63 offset0:136 offset1:138
	s_waitcnt lgkmcnt(3)
	v_mfma_f32_32x32x16_bf16 v[18:33], v[54:57], v[46:49], v[18:33]
	v_mfma_f32_32x32x16_bf16 v[2:17], v[50:53], v[46:49], v[2:17]
	ds_read2_b64 v[54:57], v62 offset0:168 offset1:170
	ds_read2_b64 v[50:53], v63 offset0:140 offset1:142
	s_waitcnt lgkmcnt(4)
	v_mfma_f32_32x32x16_bf16 v[18:33], v[58:61], v[42:45], v[18:33]
	ds_read2_b64 v[58:61], v62 offset0:172 offset1:174
	s_waitcnt lgkmcnt(4)
	v_mfma_f32_32x32x16_bf16 v[2:17], v[124:127], v[42:45], v[2:17]
	s_waitcnt lgkmcnt(3)
	v_mfma_f32_32x32x16_bf16 v[18:33], v[128:131], v[38:41], v[18:33]
	s_waitcnt lgkmcnt(2)
	v_mfma_f32_32x32x16_bf16 v[2:17], v[54:57], v[38:41], v[2:17]
	s_waitcnt lgkmcnt(1)
	v_mfma_f32_32x32x16_bf16 v[18:33], v[50:53], v[34:37], v[18:33]
	s_waitcnt lgkmcnt(0)
	v_mfma_f32_32x32x16_bf16 v[2:17], v[58:61], v[34:37], v[2:17]

; #define LAS __attribute__((address_space(3)))
; DI unsigned cvtpk(float lo, float hi) { f32x2_t v = {lo, hi}; bf16x2_t b = __builtin_convertvector(v, bf16x2_t); return __builtin_bit_cast(unsigned, b); }
; DI float fexp2(float x) { return __builtin_amdgcn_exp2f(x); }
; #define MFMA32(a, b, c) __builtin_amdgcn_mfma_f32_32x32x16_bf16((a), (b), (c), 0, 0, 0)
;     ...
;             const float mu = (m == -INFINITY) ? 0.f : m;
;             float rs = 0.f;
; #pragma unroll
;             for (int i = 0; i < 16; i += 2) {
;                 f32x2_t a2 = {s0[i], s0[i + 1]}, b2 = {s1[i], s1[i + 1]}; const f32x2_t nm = {-mu, -mu};
;                 a2 = a2 + nm; b2 = b2 + nm;
;                 s0[i] = fexp2(a2.x); s0[i + 1] = fexp2(a2.y); s1[i] = fexp2(b2.x); s1[i + 1] = fexp2(b2.y);
;                 rs += (s0[i] + s0[i + 1]) + (s1[i] + s1[i + 1]); }
;             l += rs;
;             bf16x8 pb[4];
;             { u32x4 p; p.x = cvtpk(s0[0], s0[1]); p.y = cvtpk(s0[2], s0[3]); p.z = cvtpk(s0[4], s0[5]); p.w = cvtpk(s0[6], s0[7]); pb[0] = __builtin_bit_cast(bf16x8, p);
;               p.x = cvtpk(s0[8], s0[9]); p.y = cvtpk(s0[10], s0[11]); p.z = cvtpk(s0[12], s0[13]); p.w = cvtpk(s0[14], s0[15]); pb[1] = __builtin_bit_cast(bf16x8, p);
;               p.x = cvtpk(s1[0], s1[1]); p.y = cvtpk(s1[2], s1[3]); p.z = cvtpk(s1[4], s1[5]); p.w = cvtpk(s1[6], s1[7]); pb[2] = __builtin_bit_cast(bf16x8, p);
;               p.x = cvtpk(s1[8], s1[9]); p.y = cvtpk(s1[10], s1[11]); p.z = cvtpk(s1[12], s1[13]); p.w = cvtpk(s1[14], s1[15]); pb[3] = __builtin_bit_cast(bf16x8, p); }
;             const LAS unsigned char* vb = bb + KB + n * PV + 8 * h;
; #pragma unroll
;             for (int sx = 0; sx < 4; ++sx) {
;                 const s16x4 a0 = *(const LAS s16x4*)(vb + 32 * sx), a1 = *(const LAS s16x4*)(vb + 32 * sx + 16);
;                 const s16x4 b0 = *(const LAS s16x4*)(vb + 32 * PV + 32 * sx), b1 = *(const LAS s16x4*)(vb + 32 * PV + 32 * sx + 16);
;                 o0 = MFMA32(__builtin_shufflevector(a0, a1, 0, 1, 2, 3, 4, 5, 6, 7), pb[sx], o0);
;                 o1 = MFMA32(__builtin_shufflevector(b0, b1, 0, 1, 2, 3, 4, 5, 6, 7), pb[sx], o1);
;             }
.LBB0_333:
	v_cmp_neq_f32_e32 vcc, s79, v112
	s_nop 1
	v_cndmask_b32_e64 v124, v247, -v112, vcc
	v_pk_add_f32 v[34:35], v[34:35], v[124:125] op_sel_hi:[1,0]
	v_pk_add_f32 v[50:51], v[50:51], v[124:125] op_sel_hi:[1,0]
	v_pk_add_f32 v[36:37], v[36:37], v[124:125] op_sel_hi:[1,0]
	v_pk_add_f32 v[52:53], v[52:53], v[124:125] op_sel_hi:[1,0]
	v_exp_f32_e32 v127, v34
	v_exp_f32_e32 v35, v35
	v_exp_f32_e32 v129, v50
	v_exp_f32_e32 v51, v51
	v_exp_f32_e32 v126, v36
	v_exp_f32_e32 v34, v37
	v_exp_f32_e32 v128, v52
	v_exp_f32_e32 v50, v53
	v_pk_add_f32 v[38:39], v[38:39], v[124:125] op_sel_hi:[1,0]
	v_pk_add_f32 v[36:37], v[34:35], v[126:127]
	v_exp_f32_e32 v131, v39
	v_pk_add_f32 v[52:53], v[50:51], v[128:129]
	v_pk_add_f32 v[40:41], v[40:41], v[124:125] op_sel_hi:[1,0]
	v_pk_add_f32 v[36:37], v[52:53], v[36:37]
	v_pk_add_f32 v[52:53], v[54:55], v[124:125] op_sel_hi:[1,0]
	v_exp_f32_e32 v55, v38
	v_exp_f32_e32 v54, v52
	v_exp_f32_e32 v130, v53
	v_pk_add_f32 v[52:53], v[56:57], v[124:125] op_sel_hi:[1,0]
	v_add_f32_e32 v37, 0, v37
	v_exp_f32_e32 v123, v40
	v_pk_add_f32 v[38:39], v[130:131], v[54:55]
	v_exp_f32_e32 v134, v41
	v_pk_add_f32 v[38:39], v[38:39], v[38:39] op_sel_hi:[0,1]
	v_exp_f32_e32 v135, v52
	v_exp_f32_e32 v136, v53
	v_pk_add_f32 v[40:41], v[42:43], v[124:125] op_sel_hi:[1,0]
	v_pk_add_f32 v[42:43], v[58:59], v[124:125] op_sel_hi:[1,0]
	v_add_f32_e32 v37, v36, v37
	v_exp_f32_e32 v36, v40
	v_exp_f32_e32 v38, v41
	v_exp_f32_e32 v52, v42
	v_exp_f32_e32 v56, v43
	v_add_f32_e32 v53, v134, v123
	v_add_f32_e32 v57, v136, v135
	v_pk_add_f32 v[40:41], v[38:39], v[36:37]
	v_pk_add_f32 v[42:43], v[56:57], v[52:53]
	s_nop 0
	v_pk_add_f32 v[40:41], v[42:43], v[40:41]
	v_pk_add_f32 v[42:43], v[44:45], v[124:125] op_sel_hi:[1,0]
	v_pk_add_f32 v[44:45], v[60:61], v[124:125] op_sel_hi:[1,0]
	v_exp_f32_e32 v59, v42
	v_exp_f32_e32 v61, v43
	v_exp_f32_e32 v58, v44
	v_exp_f32_e32 v60, v45
	v_pk_add_f32 v[44:45], v[62:63], v[124:125] op_sel_hi:[1,0]
	v_pk_add_f32 v[40:41], v[40:41], v[40:41] op_sel_hi:[0,1]
	v_exp_f32_e32 v53, v44
	v_exp_f32_e32 v57, v45
	v_pk_add_f32 v[42:43], v[60:61], v[58:59]
	s_nop 0
	v_pk_add_f32 v[132:133], v[42:43], v[42:43] op_sel_hi:[0,1]
	v_pk_add_f32 v[42:43], v[46:47], v[124:125] op_sel_hi:[1,0]
	v_add_f32_e32 v125, v57, v53
	v_exp_f32_e32 v37, v42
	v_exp_f32_e32 v39, v43
	v_pk_add_f32 v[42:43], v[48:49], v[124:125] op_sel_hi:[1,0]
	v_pk_add_f32 v[44:45], v[64:65], v[124:125] op_sel_hi:[1,0]
	v_exp_f32_e32 v40, v42
	v_exp_f32_e32 v132, v43
	v_exp_f32_e32 v62, v44
	v_exp_f32_e32 v124, v45
	v_add_f32_e32 v63, v39, v37
	v_pk_add_f32 v[42:43], v[132:133], v[40:41]
	v_cvt_pk_bf16_f32 v47, v126, v34
	v_pk_add_f32 v[44:45], v[124:125], v[62:63]
	v_cvt_pk_bf16_f32 v34, v52, v56
	v_pk_add_f32 v[42:43], v[44:45], v[42:43]
	v_cvt_pk_bf16_f32 v45, v40, v132
	v_cvt_pk_bf16_f32 v40, v54, v130
	v_add3_u32 v54, s43, v119, v116
	v_cvt_pk_bf16_f32 v44, v37, v39
	v_cvt_pk_bf16_f32 v37, v62, v124
	v_add_u32_e32 v62, 0x3000, v54
	v_add_f32_e32 v41, v42, v43
	v_cvt_pk_bf16_f32 v42, v36, v38
	v_cvt_pk_bf16_f32 v38, v129, v51
	v_cvt_pk_bf16_f32 v39, v128, v50
	v_cvt_pk_bf16_f32 v36, v53, v57
	ds_read2_b64 v[50:53], v62 offset0:160 offset1:162
	v_add_u32_e32 v63, 0x2000, v54
	v_cvt_pk_bf16_f32 v46, v127, v35
	v_cvt_pk_bf16_f32 v48, v55, v131
	v_cvt_pk_bf16_f32 v43, v59, v61
	v_cvt_pk_bf16_f32 v35, v58, v60
	ds_read2_b64 v[54:57], v63 offset0:128 offset1:130
	ds_read2_b64 v[58:61], v63 offset0:132 offset1:134
	v_cvt_pk_bf16_f32 v49, v123, v134
	v_add_f32_e32 v105, v105, v41
	v_cvt_pk_bf16_f32 v41, v135, v136
	ds_read2_b64 v[124:127], v62 offset0:164 offset1:166
	ds_read2_b64 v[128:131], v63 offset0:136 offset1:138
	s_waitcnt lgkmcnt(3)
	v_mfma_f32_32x32x16_bf16 v[18:33], v[54:57], v[46:49], v[18:33]
	v_mfma_f32_32x32x16_bf16 v[2:17], v[50:53], v[46:49], v[2:17]
	ds_read2_b64 v[54:57], v62 offset0:168 offset1:170
	ds_read2_b64 v[50:53], v63 offset0:140 offset1:142
	s_waitcnt lgkmcnt(4)
	v_mfma_f32_32x32x16_bf16 v[18:33], v[58:61], v[42:45], v[18:33]
	ds_read2_b64 v[58:61], v62 offset0:172 offset1:174
	s_waitcnt lgkmcnt(4)
	v_mfma_f32_32x32x16_bf16 v[2:17], v[124:127], v[42:45], v[2:17]
	s_waitcnt lgkmcnt(3)
	v_mfma_f32_32x32x16_bf16 v[18:33], v[128:131], v[38:41], v[18:33]
	s_waitcnt lgkmcnt(2)
	v_mfma_f32_32x32x16_bf16 v[2:17], v[54:57], v[38:41], v[2:17]
	s_waitcnt lgkmcnt(1)
	v_mfma_f32_32x32x16_bf16 v[18:33], v[50:53], v[34:37], v[18:33]
	s_waitcnt lgkmcnt(0)
	v_mfma_f32_32x32x16_bf16 v[2:17], v[58:61], v[34:37], v[2:17]

; #define LAS __attribute__((address_space(3)))
; DI unsigned cvtpk(float lo, float hi) { f32x2_t v = {lo, hi}; bf16x2_t b = __builtin_convertvector(v, bf16x2_t); return __builtin_bit_cast(unsigned, b); }
; DI float fexp2(float x) { return __builtin_amdgcn_exp2f(x); }
; #define MFMA32(a, b, c) __builtin_amdgcn_mfma_f32_32x32x16_bf16((a), (b), (c), 0, 0, 0)
;     ...
;             const float mu = (m == -INFINITY) ? 0.f : m;
;             float rs = 0.f;
; #pragma unroll
;             for (int i = 0; i < 16; i += 2) {
;                 f32x2_t a2 = {s0[i], s0[i + 1]}, b2 = {s1[i], s1[i + 1]}; const f32x2_t nm = {-mu, -mu};
;                 a2 = a2 + nm; b2 = b2 + nm;
;                 s0[i] = fexp2(a2.x); s0[i + 1] = fexp2(a2.y); s1[i] = fexp2(b2.x); s1[i + 1] = fexp2(b2.y);
;                 rs += (s0[i] + s0[i + 1]) + (s1[i] + s1[i + 1]); }
;             l += rs;
;             bf16x8 pb[4];
;             { u32x4 p; p.x = cvtpk(s0[0], s0[1]); p.y = cvtpk(s0[2], s0[3]); p.z = cvtpk(s0[4], s0[5]); p.w = cvtpk(s0[6], s0[7]); pb[0] = __builtin_bit_cast(bf16x8, p);
;               p.x = cvtpk(s0[8], s0[9]); p.y = cvtpk(s0[10], s0[11]); p.z = cvtpk(s0[12], s0[13]); p.w = cvtpk(s0[14], s0[15]); pb[1] = __builtin_bit_cast(bf16x8, p);
;               p.x = cvtpk(s1[0], s1[1]); p.y = cvtpk(s1[2], s1[3]); p.z = cvtpk(s1[4], s1[5]); p.w = cvtpk(s1[6], s1[7]); pb[2] = __builtin_bit_cast(bf16x8, p);
;               p.x = cvtpk(s1[8], s1[9]); p.y = cvtpk(s1[10], s1[11]); p.z = cvtpk(s1[12], s1[13]); p.w = cvtpk(s1[14], s1[15]); pb[3] = __builtin_bit_cast(bf16x8, p); }
;             const LAS unsigned char* vb = bb + KB + n * PV + 8 * h;
; #pragma unroll
;             for (int sx = 0; sx < 4; ++sx) {
;                 const s16x4 a0 = *(const LAS s16x4*)(vb + 32 * sx), a1 = *(const LAS s16x4*)(vb + 32 * sx + 16);
;                 const s16x4 b0 = *(const LAS s16x4*)(vb + 32 * PV + 32 * sx), b1 = *(const LAS s16x4*)(vb + 32 * PV + 32 * sx + 16);
;                 o0 = MFMA32(__builtin_shufflevector(a0, a1, 0, 1, 2, 3, 4, 5, 6, 7), pb[sx], o0);
;                 o1 = MFMA32(__builtin_shufflevector(b0, b1, 0, 1, 2, 3, 4, 5, 6, 7), pb[sx], o1);
;             }
.LBB0_353:
	v_cmp_neq_f32_e32 vcc, s79, v112
	s_nop 1
	v_cndmask_b32_e64 v124, v247, -v112, vcc
	v_pk_add_f32 v[34:35], v[34:35], v[124:125] op_sel_hi:[1,0]
	v_pk_add_f32 v[50:51], v[50:51], v[124:125] op_sel_hi:[1,0]
	v_pk_add_f32 v[36:37], v[36:37], v[124:125] op_sel_hi:[1,0]
	v_pk_add_f32 v[52:53], v[52:53], v[124:125] op_sel_hi:[1,0]
	v_exp_f32_e32 v127, v34
	v_exp_f32_e32 v35, v35
	v_exp_f32_e32 v129, v50
	v_exp_f32_e32 v51, v51
	v_exp_f32_e32 v126, v36
	v_exp_f32_e32 v34, v37
	v_exp_f32_e32 v128, v52
	v_exp_f32_e32 v50, v53
	v_pk_add_f32 v[38:39], v[38:39], v[124:125] op_sel_hi:[1,0]
	v_pk_add_f32 v[36:37], v[34:35], v[126:127]
	v_exp_f32_e32 v131, v39
	v_pk_add_f32 v[52:53], v[50:51], v[128:129]
	v_pk_add_f32 v[40:41], v[40:41], v[124:125] op_sel_hi:[1,0]
	v_pk_add_f32 v[36:37], v[52:53], v[36:37]
	v_pk_add_f32 v[52:53], v[54:55], v[124:125] op_sel_hi:[1,0]
	v_exp_f32_e32 v55, v38
	v_exp_f32_e32 v54, v52
	v_exp_f32_e32 v130, v53
	v_pk_add_f32 v[52:53], v[56:57], v[124:125] op_sel_hi:[1,0]
	v_add_f32_e32 v37, 0, v37
	v_exp_f32_e32 v123, v40
	v_pk_add_f32 v[38:39], v[130:131], v[54:55]
	v_exp_f32_e32 v134, v41
	v_pk_add_f32 v[38:39], v[38:39], v[38:39] op_sel_hi:[0,1]
	v_exp_f32_e32 v135, v52
	v_exp_f32_e32 v136, v53
	v_pk_add_f32 v[40:41], v[42:43], v[124:125] op_sel_hi:[1,0]
	v_pk_add_f32 v[42:43], v[58:59], v[124:125] op_sel_hi:[1,0]
	v_add_f32_e32 v37, v36, v37
	v_exp_f32_e32 v36, v40
	v_exp_f32_e32 v38, v41
	v_exp_f32_e32 v52, v42
	v_exp_f32_e32 v56, v43
	v_add_f32_e32 v53, v134, v123
	v_add_f32_e32 v57, v136, v135
	v_pk_add_f32 v[40:41], v[38:39], v[36:37]
	v_pk_add_f32 v[42:43], v[56:57], v[52:53]
	s_nop 0
	v_pk_add_f32 v[40:41], v[42:43], v[40:41]
	v_pk_add_f32 v[42:43], v[44:45], v[124:125] op_sel_hi:[1,0]
	v_pk_add_f32 v[44:45], v[60:61], v[124:125] op_sel_hi:[1,0]
	v_exp_f32_e32 v59, v42
	v_exp_f32_e32 v61, v43
	v_exp_f32_e32 v58, v44
	v_exp_f32_e32 v60, v45
	v_pk_add_f32 v[44:45], v[62:63], v[124:125] op_sel_hi:[1,0]
	v_pk_add_f32 v[40:41], v[40:41], v[40:41] op_sel_hi:[0,1]
	v_exp_f32_e32 v53, v44
	v_exp_f32_e32 v57, v45
	v_pk_add_f32 v[42:43], v[60:61], v[58:59]
	s_nop 0
	v_pk_add_f32 v[132:133], v[42:43], v[42:43] op_sel_hi:[0,1]
	v_pk_add_f32 v[42:43], v[46:47], v[124:125] op_sel_hi:[1,0]
	v_add_f32_e32 v125, v57, v53
	v_exp_f32_e32 v37, v42
	v_exp_f32_e32 v39, v43
	v_pk_add_f32 v[42:43], v[48:49], v[124:125] op_sel_hi:[1,0]
	v_pk_add_f32 v[44:45], v[64:65], v[124:125] op_sel_hi:[1,0]
	v_exp_f32_e32 v40, v42
	v_exp_f32_e32 v132, v43
	v_exp_f32_e32 v62, v44
	v_exp_f32_e32 v124, v45
	v_add_f32_e32 v63, v39, v37
	v_pk_add_f32 v[42:43], v[132:133], v[40:41]
	v_cvt_pk_bf16_f32 v47, v126, v34
	v_pk_add_f32 v[44:45], v[124:125], v[62:63]
	v_cvt_pk_bf16_f32 v34, v52, v56
	v_pk_add_f32 v[42:43], v[44:45], v[42:43]
	v_cvt_pk_bf16_f32 v45, v40, v132
	v_cvt_pk_bf16_f32 v40, v54, v130
	v_add3_u32 v54, s6, v119, v116
	v_cvt_pk_bf16_f32 v44, v37, v39
	v_cvt_pk_bf16_f32 v37, v62, v124
	v_add_u32_e32 v62, 0x3000, v54
	v_add_f32_e32 v41, v42, v43
	v_cvt_pk_bf16_f32 v42, v36, v38
	v_cvt_pk_bf16_f32 v38, v129, v51
	v_cvt_pk_bf16_f32 v39, v128, v50
	v_cvt_pk_bf16_f32 v36, v53, v57
	ds_read2_b64 v[50:53], v62 offset0:160 offset1:162
	v_add_u32_e32 v63, 0x2000, v54
	v_cvt_pk_bf16_f32 v46, v127, v35
	v_cvt_pk_bf16_f32 v48, v55, v131
	v_cvt_pk_bf16_f32 v43, v59, v61
	v_cvt_pk_bf16_f32 v35, v58, v60
	ds_read2_b64 v[54:57], v63 offset0:128 offset1:130
	ds_read2_b64 v[58:61], v63 offset0:132 offset1:134
	v_cvt_pk_bf16_f32 v49, v123, v134
	v_add_f32_e32 v105, v105, v41
	v_cvt_pk_bf16_f32 v41, v135, v136
	ds_read2_b64 v[124:127], v62 offset0:164 offset1:166
	ds_read2_b64 v[128:131], v63 offset0:136 offset1:138
	s_waitcnt lgkmcnt(3)
	v_mfma_f32_32x32x16_bf16 v[18:33], v[54:57], v[46:49], v[18:33]
	v_mfma_f32_32x32x16_bf16 v[2:17], v[50:53], v[46:49], v[2:17]
	ds_read2_b64 v[54:57], v62 offset0:168 offset1:170
	ds_read2_b64 v[50:53], v63 offset0:140 offset1:142
	s_waitcnt lgkmcnt(4)
	v_mfma_f32_32x32x16_bf16 v[18:33], v[58:61], v[42:45], v[18:33]
	ds_read2_b64 v[58:61], v62 offset0:172 offset1:174
	s_waitcnt lgkmcnt(4)
	v_mfma_f32_32x32x16_bf16 v[2:17], v[124:127], v[42:45], v[2:17]
	s_waitcnt lgkmcnt(3)
	v_mfma_f32_32x32x16_bf16 v[18:33], v[128:131], v[38:41], v[18:33]
	s_waitcnt lgkmcnt(2)
	v_mfma_f32_32x32x16_bf16 v[2:17], v[54:57], v[38:41], v[2:17]
	s_waitcnt lgkmcnt(1)
	v_mfma_f32_32x32x16_bf16 v[18:33], v[50:53], v[34:37], v[18:33]
	s_waitcnt lgkmcnt(0)
	v_mfma_f32_32x32x16_bf16 v[2:17], v[58:61], v[34:37], v[2:17]
